# rotate CU index for the KV up-projection GEMM in the MLA phase so extra tiles land on CUs with fewer Q tiles
# speedup vs baseline: 1.0044x; 1.0044x over previous
.LBB0_383:
	v_readlane_b32 s10, v255, 51
	v_readlane_b32 s0, v255, 49
	s_nop 1
	s_cmp_eq_u32 s0, 9
	s_cbranch_scc0 .Lrot_nr
	s_cmp_eq_u32 s10, 1
	s_cbranch_scc0 .Lrot_nr
	v_readlane_b32 s0, v255, 14
	s_nop 1
	s_cmpk_eq_u32 s0, 0x100
	s_cbranch_scc0 .Lrot_nr
	v_readlane_b32 s0, v255, 8
	s_nop 1
	s_xor_b32 s0, s0, 0x80
	s_nop 0
	v_writelane_b32 v255, s0, 8
.Lrot_nr:
	s_add_i32 s10, s10, 1
	v_readlane_b32 s0, v255, 21
	s_cmp_eq_u32 s10, s0
	s_cbranch_scc1 .LBB0_792
.LBB0_384:
	v_readlane_b32 s0, v255, 33
	v_readlane_b32 s1, v255, 34
	s_andn2_b64 vcc, exec, s[0:1]
	s_cbranch_vccnz .LBB0_386
	s_cmp_lg_u32 s10, 0
	s_cbranch_scc0 .Lrot_skip
	v_readlane_b32 s0, v255, 14
	s_nop 1
	s_cmpk_eq_u32 s0, 0x100
	s_cbranch_scc0 .Lrot_skip
	v_readlane_b32 s0, v255, 8
	s_nop 1
	s_xor_b32 s0, s0, 0x80
	s_nop 0
	v_writelane_b32 v255, s0, 8
.Lrot_skip:
	s_mov_b32 s0, 0
	s_cmp_lg_u32 s10, 0
	v_writelane_b32 v255, s0, 31
	s_cselect_b64 s[0:1], -1, 0
	v_cndmask_b32_e64 v214, 0, 1, s[0:1]
	s_and_b64 s[0:1], s[0:1], exec
	s_movk_i32 s2, 0x6800
	s_cselect_b32 s2, s2, 0x6000
	v_writelane_b32 v255, s2, 48
	s_movk_i32 s2, 0x800
	s_cselect_b32 s47, s2, 0x600
	s_movk_i32 s2, 0x180
	s_cselect_b32 s2, 0x100, s2
	v_writelane_b32 v255, s2, 29
	s_mov_b32 s0, 0x12c00000
	s_cselect_b32 s0, s0, 0x11a00000
	v_writelane_b32 v255, s3, 30
	v_readlane_b32 s2, v252, 14
	s_mov_b32 s1, 0x2600000
	v_readlane_b32 s3, v252, 15
	s_cselect_b32 s26, s2, s22
	s_movk_i32 s2, 0xa00
	s_cselect_b32 s1, s1, 0x2400000
	s_cselect_b32 s27, s3, s23
	s_cselect_b32 s15, s2, 0x600
	s_add_u32 s24, s74, s0
	s_addc_u32 s25, s75, 0
	s_add_u32 s50, s74, s1
	s_mov_b64 s[0:1], 0
	v_writelane_b32 v255, s0, 27
	s_addc_u32 s51, s75, 0
	s_mov_b32 s46, 1
	v_writelane_b32 v255, s1, 28
	s_mov_b32 s0, 0
	v_writelane_b32 v255, s0, 20
	v_writelane_b32 v255, s0, 32
